# input prep and final RMSNorm: once-read f32 row loads and final output stores issued nt
# speedup vs baseline: 1.0069x; 1.0069x over previous
; DEVI int otid() { int t = threadIdx.x; asm volatile("" : "+v"(t)); return t; }
; DEVI int obid() { int t = blockIdx.x; asm volatile("" : "+s"(t)); return t; }
; DEVI u32x2 pk4(f32x4 v) { u32x2 r; r.x = cvt_pk(v[0], v[1]); r.y = cvt_pk(v[2], v[3]); return r; }
; DEVI void prep_phase(const float* src, u16* dst, float* ssq) {
;     const int lane = otid() & 63, gw = obid() * 8 + (otid() >> 6), nw = gridDim.x * 8;
;     for (int r = gw; r < T_TOK; r += nw) {
;         const float* s = src + (size_t)r * DM; f32x4 v[4]; float ss = 0.f;
; #pragma unroll
;         for (int i = 0; i < 4; ++i) { v[i] = *(const f32x4*)(s + i * 256 + lane * 4); ss += v[i][0] * v[i][0] + v[i][1] * v[i][1] + v[i][2] * v[i][2] + v[i][3] * v[i][3]; }
; #pragma unroll
;         for (int o = 32; o > 0; o >>= 1) ss += __shfl_xor(ss, o);
; #pragma unroll
;         for (int i = 0; i < 4; ++i) *(u32x2*)(dst + (size_t)r * DM + i * 256 + lane * 4) = pk4(v[i]);
;         if (lane == 0) *(f32x4*)(ssq + (size_t)r * 4) = (f32x4){ss, 0.f, 0.f, 0.f};
;     }
.LBB0_204:
	global_load_dwordx4 v[18:21], v[8:9], off offset:-3072 nt
	global_load_dwordx4 v[22:25], v[8:9], off offset:-2048 nt
	global_load_dwordx4 v[26:29], v[8:9], off offset:-1024 nt
	global_load_dwordx4 v[30:33], v[8:9], off nt
	v_lshl_add_u64 v[34:35], v[8:9], 0, s[12:13]
	v_lshl_add_u64 v[52:53], v[6:7], 0, s[10:11]
	v_lshl_add_u64 v[54:55], v[4:5], 0, s[8:9]
	global_load_dwordx4 v[36:39], v[34:35], off offset:-3072 nt
	global_load_dwordx4 v[40:43], v[34:35], off offset:-2048 nt
	global_load_dwordx4 v[44:47], v[34:35], off offset:-1024 nt
	global_load_dwordx4 v[48:51], v[34:35], off nt
	s_waitcnt vmcnt(4)
	v_mul_f32_e32 v0, v19, v19
	s_waitcnt lgkmcnt(0)
	v_mul_f32_e32 v2, v23, v23
	v_mul_f32_e32 v3, v27, v27
	v_fmac_f32_e32 v0, v18, v18
	v_fmac_f32_e32 v2, v22, v22
	v_mul_f32_e32 v17, v31, v31
	v_fmac_f32_e32 v3, v26, v26
	v_fmac_f32_e32 v0, v20, v20
	v_fmac_f32_e32 v2, v24, v24
	v_fmac_f32_e32 v17, v30, v30
	v_fmac_f32_e32 v3, v28, v28
	v_fmac_f32_e32 v0, v21, v21
	v_fmac_f32_e32 v2, v25, v25
	v_fmac_f32_e32 v17, v32, v32
	v_fmac_f32_e32 v3, v29, v29
	v_add_f32_e32 v0, v0, v2
	v_fmac_f32_e32 v17, v33, v33
	v_add_f32_e32 v0, v0, v3
	v_add_f32_e32 v0, v0, v17
	ds_bpermute_b32 v2, v11, v0
	v_cvt_pk_bf16_f32 v3, v20, v21
	v_cvt_pk_bf16_f32 v20, v26, v27
	v_cvt_pk_bf16_f32 v21, v28, v29
	s_waitcnt lgkmcnt(0)
	v_add_f32_e32 v0, v0, v2
	ds_bpermute_b32 v2, v12, v0
	s_waitcnt lgkmcnt(0)
	v_add_f32_e32 v0, v0, v2
	ds_bpermute_b32 v2, v13, v0
	s_waitcnt lgkmcnt(0)
	v_add_f32_e32 v0, v0, v2
	ds_bpermute_b32 v17, v14, v0
	v_cvt_pk_bf16_f32 v2, v18, v19
	v_cvt_pk_bf16_f32 v18, v22, v23
	v_cvt_pk_bf16_f32 v19, v24, v25
	global_store_dwordx2 v[6:7], v[2:3], off offset:-1024
	global_store_dwordx2 v[6:7], v[18:19], off offset:-512
	s_waitcnt lgkmcnt(0)
	v_add_f32_e32 v0, v0, v17
	ds_bpermute_b32 v17, v15, v0
	v_cvt_pk_bf16_f32 v18, v30, v31
	v_cvt_pk_bf16_f32 v19, v32, v33
	global_store_dwordx2 v[6:7], v[20:21], off
	global_store_dwordx2 v[6:7], v[18:19], off offset:512
	s_waitcnt lgkmcnt(0)
	v_add_f32_e32 v0, v0, v17
	ds_bpermute_b32 v2, v16, v0
	s_and_saveexec_b64 s[0:1], vcc
	s_cbranch_execz .Lprep_a
	s_waitcnt lgkmcnt(0)
	v_add_f32_e32 v0, v0, v2
	v_mov_b32_e32 v2, v1
	v_mov_b32_e32 v3, v1
	global_store_dwordx4 v[4:5], v[0:3], off

; DEVI int otid() { int t = threadIdx.x; asm volatile("" : "+v"(t)); return t; }
; DEVI int obid() { int t = blockIdx.x; asm volatile("" : "+s"(t)); return t; }
; DEVI void rms_final(float* io, const float* g) {
;     const int lane = otid() & 63, gw = obid() * 8 + (otid() >> 6), nw = gridDim.x * 8;
;     f32x4 gv[4];
; #pragma unroll
;     for (int i = 0; i < 4; ++i) gv[i] = *(const f32x4*)(g + i * 256 + lane * 4);
;     for (int r = gw; r < T_TOK; r += nw) {
;         float* s = io + (size_t)r * DM; f32x4 v[4]; float ss = 0.f;
; #pragma unroll
;         for (int i = 0; i < 4; ++i) { v[i] = *(const f32x4*)(s + i * 256 + lane * 4); ss += v[i][0] * v[i][0] + v[i][1] * v[i][1] + v[i][2] * v[i][2] + v[i][3] * v[i][3]; }
; #pragma unroll
;         for (int o = 32; o > 0; o >>= 1) ss += __shfl_xor(ss, o);
;         const float rs = rsqrtf(ss * (1.f / DM) + 1e-6f);
; #pragma unroll
;         for (int i = 0; i < 4; ++i) *(f32x4*)(s + i * 256 + lane * 4) = v[i] * rs * gv[i];
;     }
.LBB0_1818:
	global_load_dwordx4 v[26:29], v[16:17], off offset:-3072 nt
	global_load_dwordx4 v[30:33], v[16:17], off offset:-2048 nt
	global_load_dwordx4 v[34:37], v[16:17], off offset:-1024 nt
	global_load_dwordx4 v[38:41], v[16:17], off nt
	v_lshl_add_u64 v[58:59], v[16:17], 0, s[2:3]
	global_load_dwordx4 v[60:63], v[58:59], off offset:-3072 nt
	global_load_dwordx4 v[64:67], v[58:59], off offset:-2048 nt
	global_load_dwordx4 v[68:71], v[58:59], off offset:-1024 nt
	global_load_dwordx4 v[72:75], v[58:59], off nt
	v_add_u32_e32 v18, s20, v18
	v_add_u32_e32 v18, s20, v18
	v_cmp_lt_i32_e64 s[0:1], s7, v18
	s_or_b64 s[4:5], s[0:1], s[4:5]
	s_waitcnt vmcnt(7)
	v_mov_b32_e32 v44, v27
	s_waitcnt vmcnt(6)
	v_mov_b32_e32 v45, v31
	v_mov_b32_e32 v42, v26
	v_mov_b32_e32 v43, v30
	s_waitcnt vmcnt(5)
	v_mov_b32_e32 v52, v35
	s_waitcnt vmcnt(4)
	v_mov_b32_e32 v53, v39
	v_pk_mul_f32 v[44:45], v[44:45], v[44:45]
	v_mov_b32_e32 v46, v28
	v_mov_b32_e32 v47, v32
	v_mov_b32_e32 v50, v34
	v_mov_b32_e32 v51, v38
	v_pk_mul_f32 v[52:53], v[52:53], v[52:53]
	v_pk_fma_f32 v[42:43], v[42:43], v[42:43], v[44:45]
	v_mov_b32_e32 v48, v29
	v_mov_b32_e32 v49, v33
	v_mov_b32_e32 v54, v36
	v_mov_b32_e32 v55, v40
	v_pk_fma_f32 v[44:45], v[50:51], v[50:51], v[52:53]
	v_pk_fma_f32 v[42:43], v[46:47], v[46:47], v[42:43]
	v_mov_b32_e32 v56, v37
	v_mov_b32_e32 v57, v41
	v_pk_fma_f32 v[44:45], v[54:55], v[54:55], v[44:45]
	v_pk_fma_f32 v[42:43], v[48:49], v[48:49], v[42:43]
	v_pk_fma_f32 v[44:45], v[56:57], v[56:57], v[44:45]
	v_add_f32_e32 v42, v42, v43
	v_add_f32_e32 v42, v42, v44
	v_add_f32_e32 v42, v42, v45
	ds_bpermute_b32 v43, v19, v42
	s_waitcnt lgkmcnt(0)
	v_add_f32_e32 v42, v42, v43
	ds_bpermute_b32 v43, v20, v42
	s_waitcnt lgkmcnt(0)
	v_add_f32_e32 v42, v42, v43
	ds_bpermute_b32 v43, v21, v42
	s_waitcnt lgkmcnt(0)
	v_add_f32_e32 v42, v42, v43
	ds_bpermute_b32 v43, v22, v42
	s_waitcnt lgkmcnt(0)
	v_add_f32_e32 v42, v42, v43
	ds_bpermute_b32 v43, v23, v42
	s_waitcnt lgkmcnt(0)
	v_add_f32_e32 v42, v42, v43
	ds_bpermute_b32 v43, v24, v42
	s_waitcnt lgkmcnt(0)
	v_add_f32_e32 v42, v42, v43
	v_fmamk_f32 v42, v42, 0x3a800000, v25
	v_mul_f32_e32 v43, 0x4b800000, v42
	v_cmp_gt_f32_e32 vcc, s6, v42
	s_nop 1
	v_cndmask_b32_e32 v42, v42, v43, vcc
	v_rsq_f32_e32 v42, v42
	s_nop 0
	v_mul_f32_e32 v43, 0x45800000, v42
	v_cndmask_b32_e32 v42, v42, v43, vcc
	v_pk_mul_f32 v[26:27], v[26:27], v[42:43] op_sel_hi:[1,0]
	v_pk_mul_f32 v[28:29], v[28:29], v[42:43] op_sel_hi:[1,0]
	v_pk_mul_f32 v[30:31], v[30:31], v[42:43] op_sel_hi:[1,0]
	v_pk_mul_f32 v[32:33], v[32:33], v[42:43] op_sel_hi:[1,0]
	v_pk_mul_f32 v[34:35], v[34:35], v[42:43] op_sel_hi:[1,0]
	v_pk_mul_f32 v[36:37], v[36:37], v[42:43] op_sel_hi:[1,0]
	v_pk_mul_f32 v[38:39], v[38:39], v[42:43] op_sel_hi:[1,0]
	v_pk_mul_f32 v[40:41], v[40:41], v[42:43] op_sel_hi:[1,0]
	v_pk_mul_f32 v[28:29], v[2:3], v[28:29]
	v_pk_mul_f32 v[26:27], v[0:1], v[26:27]
	v_pk_mul_f32 v[32:33], v[6:7], v[32:33]
	v_pk_mul_f32 v[30:31], v[4:5], v[30:31]
	v_pk_mul_f32 v[36:37], v[10:11], v[36:37]
	v_pk_mul_f32 v[34:35], v[8:9], v[34:35]
	v_pk_mul_f32 v[40:41], v[14:15], v[40:41]
	v_pk_mul_f32 v[38:39], v[12:13], v[38:39]
	global_store_dwordx4 v[16:17], v[26:29], off offset:-3072 nt
	global_store_dwordx4 v[16:17], v[30:33], off offset:-2048 nt
	global_store_dwordx4 v[16:17], v[34:37], off offset:-1024 nt
	global_store_dwordx4 v[16:17], v[38:41], off nt
	s_waitcnt vmcnt(7)
	v_mov_b32_e32 v44, v61
	s_waitcnt vmcnt(6)
	v_mov_b32_e32 v45, v65
	v_mov_b32_e32 v42, v60
	v_mov_b32_e32 v43, v64
	s_waitcnt vmcnt(5)
	v_mov_b32_e32 v52, v69
	s_waitcnt vmcnt(4)
	v_mov_b32_e32 v53, v73
	v_pk_mul_f32 v[44:45], v[44:45], v[44:45]
	v_mov_b32_e32 v46, v62
	v_mov_b32_e32 v47, v66
	v_mov_b32_e32 v50, v68
	v_mov_b32_e32 v51, v72
	v_pk_mul_f32 v[52:53], v[52:53], v[52:53]
	v_pk_fma_f32 v[42:43], v[42:43], v[42:43], v[44:45]
	v_mov_b32_e32 v48, v63
	v_mov_b32_e32 v49, v67
	v_mov_b32_e32 v54, v70
	v_mov_b32_e32 v55, v74
	v_pk_fma_f32 v[44:45], v[50:51], v[50:51], v[52:53]
	v_pk_fma_f32 v[42:43], v[46:47], v[46:47], v[42:43]
	v_mov_b32_e32 v56, v71
	v_mov_b32_e32 v57, v75
	v_pk_fma_f32 v[44:45], v[54:55], v[54:55], v[44:45]
	v_pk_fma_f32 v[42:43], v[48:49], v[48:49], v[42:43]
	v_pk_fma_f32 v[44:45], v[56:57], v[56:57], v[44:45]
	v_add_f32_e32 v42, v42, v43
	v_add_f32_e32 v42, v42, v44
	v_add_f32_e32 v42, v42, v45
	ds_bpermute_b32 v43, v19, v42
	s_waitcnt lgkmcnt(0)
	v_add_f32_e32 v42, v42, v43
	ds_bpermute_b32 v43, v20, v42
	s_waitcnt lgkmcnt(0)
	v_add_f32_e32 v42, v42, v43
	ds_bpermute_b32 v43, v21, v42
	s_waitcnt lgkmcnt(0)
	v_add_f32_e32 v42, v42, v43
	ds_bpermute_b32 v43, v22, v42
	s_waitcnt lgkmcnt(0)
	v_add_f32_e32 v42, v42, v43
	ds_bpermute_b32 v43, v23, v42
	s_waitcnt lgkmcnt(0)
	v_add_f32_e32 v42, v42, v43
	ds_bpermute_b32 v43, v24, v42
	s_waitcnt lgkmcnt(0)
	v_add_f32_e32 v42, v42, v43
	v_fmamk_f32 v42, v42, 0x3a800000, v25
	v_mul_f32_e32 v43, 0x4b800000, v42
	v_cmp_gt_f32_e32 vcc, s6, v42
	s_nop 1
	v_cndmask_b32_e32 v42, v42, v43, vcc
	v_rsq_f32_e32 v42, v42
	s_nop 0
	v_mul_f32_e32 v43, 0x45800000, v42
	v_cndmask_b32_e32 v42, v42, v43, vcc
	v_pk_mul_f32 v[60:61], v[60:61], v[42:43] op_sel_hi:[1,0]
	v_pk_mul_f32 v[62:63], v[62:63], v[42:43] op_sel_hi:[1,0]
	v_pk_mul_f32 v[64:65], v[64:65], v[42:43] op_sel_hi:[1,0]
	v_pk_mul_f32 v[66:67], v[66:67], v[42:43] op_sel_hi:[1,0]
	v_pk_mul_f32 v[68:69], v[68:69], v[42:43] op_sel_hi:[1,0]
	v_pk_mul_f32 v[70:71], v[70:71], v[42:43] op_sel_hi:[1,0]
	v_pk_mul_f32 v[72:73], v[72:73], v[42:43] op_sel_hi:[1,0]
	v_pk_mul_f32 v[74:75], v[74:75], v[42:43] op_sel_hi:[1,0]
	v_pk_mul_f32 v[62:63], v[2:3], v[62:63]
	v_pk_mul_f32 v[60:61], v[0:1], v[60:61]
	v_pk_mul_f32 v[66:67], v[6:7], v[66:67]
	v_pk_mul_f32 v[64:65], v[4:5], v[64:65]
	v_pk_mul_f32 v[70:71], v[10:11], v[70:71]
	v_pk_mul_f32 v[68:69], v[8:9], v[68:69]
	v_pk_mul_f32 v[74:75], v[14:15], v[74:75]
	v_pk_mul_f32 v[72:73], v[12:13], v[72:73]
	global_store_dwordx4 v[58:59], v[60:63], off offset:-3072 nt
	global_store_dwordx4 v[58:59], v[64:67], off offset:-2048 nt
	global_store_dwordx4 v[58:59], v[68:71], off offset:-1024 nt
	global_store_dwordx4 v[58:59], v[72:75], off nt
	v_lshl_add_u64 v[16:17], v[16:17], 0, s[2:3]
	v_lshl_add_u64 v[16:17], v[16:17], 0, s[2:3]
	s_andn2_b64 exec, exec, s[4:5]
	s_cbranch_execnz .LBB0_1818
